# SwiGLU main phase's last K-iteration prefetches the tail half-unit's K-tiles 0/1; SwiGLU tail prologue staging loads removed
# baseline (speedup 1.0000x reference)
.LBB0_255:
	s_and_b32 s98, s2, 15
	s_add_i32 s98, s98, 0xb0
	s_lshl_b32 s98, s98, 18
	s_add_u32 s98, s31, s98
	s_addc_u32 s99, s34, 0
	s_lshr_b32 s100, s2, 4
	s_add_i32 s100, s100, 14
	s_lshl_b32 s100, s100, 19
	s_add_u32 s100, s35, s100
	s_addc_u32 s101, s36, 0
	s_ashr_i32 s15, s14, 31
	s_lshl_b64 s[20:21], s[14:15], 19
	s_add_u32 s42, s31, s20
	s_addc_u32 s43, s34, s21
	s_and_b64 s[20:21], s[4:5], exec
	s_cselect_b32 s15, s43, s99
	s_cselect_b32 s20, s42, s98
	s_ashr_i32 s13, s12, 31
	s_lshl_b64 s[50:51], s[12:13], 19
	s_add_u32 s50, s35, s50
	s_addc_u32 s51, s36, s51
	s_and_b64 s[58:59], s[4:5], exec
	s_cselect_b32 s13, s51, s101
	s_cselect_b32 s21, s50, s100
	s_add_u32 s52, s52, 0x40080
	s_addc_u32 s53, s53, 0
	s_add_u32 s73, s56, 0x100
	s_addc_u32 s75, s57, 0
	s_mov_b32 s82, -2
	s_add_u32 s0, s52, 0xfffc0080
	s_addc_u32 s56, s53, -1
	s_add_i32 s83, 0, 0x10000
	s_cmp_eq_u32 s82, 12
	s_cselect_b32 s59, s15, s56
	s_cselect_b32 s58, s20, s0
	s_cselect_b32 s57, s13, s75
	s_cselect_b32 s56, s21, s73
	s_add_i32 s0, 0, 0x14000
	v_add_u32_e32 v94, s83, v171
	v_add_u32_e32 v155, s0, v171
	ds_read_b128 v[74:77], v94
	ds_read_b128 v[78:81], v94 offset:1024
	ds_read_b128 v[90:93], v94 offset:2048
	ds_read_b128 v[94:97], v94 offset:3072
	ds_read_b128 v[180:183], v155
	ds_read_b128 v[184:187], v155 offset:1024
	ds_read_b128 v[188:191], v155 offset:2048
	ds_read_b128 v[192:195], v155 offset:3072
	v_lshl_add_u64 v[168:169], s[52:53], 0, v[164:165]
	s_add_i32 m0, s61, 0xc000
	ds_read_b128 v[196:199], v177
	ds_read_b128 v[200:203], v177 offset:1024
	ds_read_b128 v[204:207], v177 offset:2048
	ds_read_b128 v[208:211], v177 offset:3072
	ds_read_b128 v[212:215], v177 offset:4096
	ds_read_b128 v[216:219], v177 offset:5120
	ds_read_b128 v[230:233], v177 offset:6144
	ds_read_b128 v[238:241], v177 offset:7168
	global_load_lds_dwordx4 v[168:169], off
	v_lshl_add_u64 v[168:169], s[52:53], 0, v[166:167]
	s_add_i32 m0, s61, 0xe000
	s_nop 0
	global_load_lds_dwordx4 v[168:169], off
	s_waitcnt vmcnt(8)
	s_waitcnt lgkmcnt(0)
	s_barrier
	s_setprio 1
	s_waitcnt lgkmcnt(0)
	v_mfma_f32_16x16x32_bf16 v[142:145], v[74:77], v[196:199], 0
	v_mfma_f32_16x16x32_bf16 v[134:137], v[90:93], v[196:199], 0
	v_mfma_f32_16x16x32_bf16 v[118:121], v[90:93], v[204:207], 0
	v_mfma_f32_16x16x32_bf16 v[126:129], v[74:77], v[204:207], 0
	v_mfma_f32_16x16x32_bf16 v[110:113], v[74:77], v[212:215], 0
	v_mfma_f32_16x16x32_bf16 v[102:105], v[90:93], v[212:215], 0
	v_mfma_f32_16x16x32_bf16 v[70:73], v[90:93], v[230:233], 0
	v_mfma_f32_16x16x32_bf16 v[86:89], v[74:77], v[230:233], 0
	v_mfma_f32_16x16x32_bf16 v[142:145], v[78:81], v[200:203], v[142:145]
	v_mfma_f32_16x16x32_bf16 v[134:137], v[94:97], v[200:203], v[134:137]
	v_mfma_f32_16x16x32_bf16 v[118:121], v[94:97], v[208:211], v[118:121]
	v_mfma_f32_16x16x32_bf16 v[126:129], v[78:81], v[208:211], v[126:129]
	v_mfma_f32_16x16x32_bf16 v[110:113], v[78:81], v[216:219], v[110:113]
	v_mfma_f32_16x16x32_bf16 v[102:105], v[94:97], v[216:219], v[102:105]
	v_mfma_f32_16x16x32_bf16 v[70:73], v[94:97], v[238:241], v[70:73]
	v_mfma_f32_16x16x32_bf16 v[86:89], v[78:81], v[238:241], v[86:89]
	s_setprio 0
	s_setprio 1
	v_mfma_f32_16x16x32_bf16 v[138:141], v[180:183], v[196:199], 0
	v_mfma_f32_16x16x32_bf16 v[130:133], v[188:191], v[196:199], 0
	v_mfma_f32_16x16x32_bf16 v[114:117], v[188:191], v[204:207], 0
	v_mfma_f32_16x16x32_bf16 v[122:125], v[180:183], v[204:207], 0
	v_mfma_f32_16x16x32_bf16 v[106:109], v[180:183], v[212:215], 0
	v_mfma_f32_16x16x32_bf16 v[98:101], v[188:191], v[212:215], 0
	v_mfma_f32_16x16x32_bf16 v[66:69], v[188:191], v[230:233], 0
	v_mfma_f32_16x16x32_bf16 v[82:85], v[180:183], v[230:233], 0
	v_mfma_f32_16x16x32_bf16 v[138:141], v[184:187], v[200:203], v[138:141]
	v_mfma_f32_16x16x32_bf16 v[130:133], v[192:195], v[200:203], v[130:133]
	v_mfma_f32_16x16x32_bf16 v[114:117], v[192:195], v[208:211], v[114:117]
	v_mfma_f32_16x16x32_bf16 v[122:125], v[184:187], v[208:211], v[122:125]
	v_mfma_f32_16x16x32_bf16 v[106:109], v[184:187], v[216:219], v[106:109]
	v_mfma_f32_16x16x32_bf16 v[98:101], v[192:195], v[216:219], v[98:101]
	v_mfma_f32_16x16x32_bf16 v[66:69], v[192:195], v[238:241], v[66:69]
	v_mfma_f32_16x16x32_bf16 v[82:85], v[184:187], v[238:241], v[82:85]
	s_setprio 0
	s_barrier
	s_add_i32 s83, s83, s37
	v_lshl_add_u64 v[168:169], s[56:57], 0, v[150:151]
	s_mov_b32 m0, s83
	ds_read_b128 v[196:199], v177 offset:16384
	ds_read_b128 v[200:203], v177 offset:17408
	ds_read_b128 v[204:207], v177 offset:18432
	ds_read_b128 v[208:211], v177 offset:19456
	ds_read_b128 v[212:215], v177 offset:20480
	ds_read_b128 v[216:219], v177 offset:21504
	ds_read_b128 v[230:233], v177 offset:22528
	ds_read_b128 v[238:241], v177 offset:23552
	global_load_lds_dwordx4 v[168:169], off
	s_add_i32 m0, s83, 0x2000
	s_add_u32 s84, s56, 0x40000
	v_lshl_add_u64 v[242:243], s[56:57], 0, v[146:147]
	s_addc_u32 s85, s57, 0
	s_add_i32 s0, s0, s37
	global_load_lds_dwordx4 v[242:243], off
	v_lshl_add_u64 v[244:245], s[84:85], 0, v[150:151]
	s_mov_b32 m0, s0
	v_lshl_add_u64 v[246:247], s[58:59], 0, v[148:149]
	global_load_lds_dwordx4 v[244:245], off
	v_lshl_add_u64 v[244:245], s[84:85], 0, v[146:147]
	s_add_i32 m0, s0, 0x2000
	s_nop 0
	global_load_lds_dwordx4 v[244:245], off
	v_lshl_add_u64 v[244:245], s[58:59], 0, v[152:153]
	s_mov_b32 m0, s61
	s_nop 0
	global_load_lds_dwordx4 v[244:245], off
	s_mov_b32 m0, s64
	s_nop 0
	global_load_lds_dwordx4 v[246:247], off
	s_waitcnt vmcnt(8)
	s_waitcnt lgkmcnt(0)
	s_barrier
	s_setprio 1
	s_waitcnt lgkmcnt(0)
	v_mfma_f32_16x16x32_bf16 v[62:65], v[74:77], v[196:199], 0
	v_mfma_f32_16x16x32_bf16 v[54:57], v[90:93], v[196:199], 0
	v_mfma_f32_16x16x32_bf16 v[38:41], v[90:93], v[204:207], 0
	v_mfma_f32_16x16x32_bf16 v[46:49], v[74:77], v[204:207], 0
	v_mfma_f32_16x16x32_bf16 v[30:33], v[74:77], v[212:215], 0
	v_mfma_f32_16x16x32_bf16 v[22:25], v[90:93], v[212:215], 0
	v_mfma_f32_16x16x32_bf16 v[6:9], v[90:93], v[230:233], 0
	v_mfma_f32_16x16x32_bf16 v[14:17], v[74:77], v[230:233], 0
	v_mfma_f32_16x16x32_bf16 v[62:65], v[78:81], v[200:203], v[62:65]
	v_mfma_f32_16x16x32_bf16 v[54:57], v[94:97], v[200:203], v[54:57]
	v_mfma_f32_16x16x32_bf16 v[38:41], v[94:97], v[208:211], v[38:41]
	v_mfma_f32_16x16x32_bf16 v[46:49], v[78:81], v[208:211], v[46:49]
	v_mfma_f32_16x16x32_bf16 v[30:33], v[78:81], v[216:219], v[30:33]
	v_mfma_f32_16x16x32_bf16 v[22:25], v[94:97], v[216:219], v[22:25]
	v_mfma_f32_16x16x32_bf16 v[6:9], v[94:97], v[238:241], v[6:9]
	v_mfma_f32_16x16x32_bf16 v[14:17], v[78:81], v[238:241], v[14:17]
	s_setprio 0
	s_setprio 1
	v_mfma_f32_16x16x32_bf16 v[58:61], v[180:183], v[196:199], 0
	v_mfma_f32_16x16x32_bf16 v[50:53], v[188:191], v[196:199], 0
	v_mfma_f32_16x16x32_bf16 v[34:37], v[188:191], v[204:207], 0
	v_mfma_f32_16x16x32_bf16 v[42:45], v[180:183], v[204:207], 0
	v_mfma_f32_16x16x32_bf16 v[26:29], v[180:183], v[212:215], 0
	v_mfma_f32_16x16x32_bf16 v[18:21], v[188:191], v[212:215], 0
	v_mfma_f32_16x16x32_bf16 v[2:5], v[188:191], v[230:233], 0
	v_mfma_f32_16x16x32_bf16 v[10:13], v[180:183], v[230:233], 0
	v_mfma_f32_16x16x32_bf16 v[58:61], v[184:187], v[200:203], v[58:61]
	v_mfma_f32_16x16x32_bf16 v[50:53], v[192:195], v[200:203], v[50:53]
	v_mfma_f32_16x16x32_bf16 v[34:37], v[192:195], v[208:211], v[34:37]
	v_mfma_f32_16x16x32_bf16 v[42:45], v[184:187], v[208:211], v[42:45]
	v_mfma_f32_16x16x32_bf16 v[26:29], v[184:187], v[216:219], v[26:29]
	v_mfma_f32_16x16x32_bf16 v[18:21], v[192:195], v[216:219], v[18:21]
	v_mfma_f32_16x16x32_bf16 v[2:5], v[192:195], v[238:241], v[2:5]
	v_mfma_f32_16x16x32_bf16 v[10:13], v[184:187], v[238:241], v[10:13]
	s_setprio 0
	s_barrier
	s_add_i32 s0, 0, 0x18000
	s_add_i32 s83, 0, 0x1c000
	v_add_u32_e32 v94, s0, v171
	v_add_u32_e32 v155, s83, v171
	ds_read_b128 v[74:77], v94
	ds_read_b128 v[78:81], v94 offset:1024
	ds_read_b128 v[90:93], v94 offset:2048
	ds_read_b128 v[94:97], v94 offset:3072
	ds_read_b128 v[180:183], v155
	ds_read_b128 v[184:187], v155 offset:1024
	ds_read_b128 v[188:191], v155 offset:2048
	ds_read_b128 v[192:195], v155 offset:3072
	s_add_u32 s58, s58, 0x40000
	s_addc_u32 s59, s59, 0
	s_mov_b32 m0, s65
	v_lshl_add_u64 v[248:249], s[58:59], 0, v[152:153]
	ds_read_b128 v[196:199], v177 offset:32768
	ds_read_b128 v[200:203], v177 offset:33792
	ds_read_b128 v[204:207], v177 offset:34816
	ds_read_b128 v[208:211], v177 offset:35840
	ds_read_b128 v[212:215], v177 offset:36864
	ds_read_b128 v[216:219], v177 offset:37888
	ds_read_b128 v[230:233], v177 offset:38912
	ds_read_b128 v[238:241], v177 offset:39936
	global_load_lds_dwordx4 v[248:249], off
	v_lshl_add_u64 v[248:249], s[58:59], 0, v[148:149]
	s_mov_b32 m0, s66
	s_nop 0
	global_load_lds_dwordx4 v[248:249], off
	s_waitcnt vmcnt(8)
	s_waitcnt lgkmcnt(0)
	s_barrier
	s_setprio 1
	s_waitcnt lgkmcnt(0)
	v_mfma_f32_16x16x32_bf16 v[142:145], v[74:77], v[196:199], v[142:145]
	v_mfma_f32_16x16x32_bf16 v[134:137], v[90:93], v[196:199], v[134:137]
	v_mfma_f32_16x16x32_bf16 v[118:121], v[90:93], v[204:207], v[118:121]
	v_mfma_f32_16x16x32_bf16 v[126:129], v[74:77], v[204:207], v[126:129]
	v_mfma_f32_16x16x32_bf16 v[110:113], v[74:77], v[212:215], v[110:113]
	v_mfma_f32_16x16x32_bf16 v[102:105], v[90:93], v[212:215], v[102:105]
	v_mfma_f32_16x16x32_bf16 v[70:73], v[90:93], v[230:233], v[70:73]
	v_mfma_f32_16x16x32_bf16 v[86:89], v[74:77], v[230:233], v[86:89]
	v_mfma_f32_16x16x32_bf16 v[142:145], v[78:81], v[200:203], v[142:145]
	v_mfma_f32_16x16x32_bf16 v[134:137], v[94:97], v[200:203], v[134:137]
	v_mfma_f32_16x16x32_bf16 v[118:121], v[94:97], v[208:211], v[118:121]
	v_mfma_f32_16x16x32_bf16 v[126:129], v[78:81], v[208:211], v[126:129]
	v_mfma_f32_16x16x32_bf16 v[110:113], v[78:81], v[216:219], v[110:113]
	v_mfma_f32_16x16x32_bf16 v[102:105], v[94:97], v[216:219], v[102:105]
	v_mfma_f32_16x16x32_bf16 v[70:73], v[94:97], v[238:241], v[70:73]
	v_mfma_f32_16x16x32_bf16 v[86:89], v[78:81], v[238:241], v[86:89]
	s_setprio 0
	s_setprio 1
	v_mfma_f32_16x16x32_bf16 v[138:141], v[180:183], v[196:199], v[138:141]
	v_mfma_f32_16x16x32_bf16 v[130:133], v[188:191], v[196:199], v[130:133]
	v_mfma_f32_16x16x32_bf16 v[114:117], v[188:191], v[204:207], v[114:117]
	v_mfma_f32_16x16x32_bf16 v[122:125], v[180:183], v[204:207], v[122:125]
	v_mfma_f32_16x16x32_bf16 v[106:109], v[180:183], v[212:215], v[106:109]
	v_mfma_f32_16x16x32_bf16 v[98:101], v[188:191], v[212:215], v[98:101]
	v_mfma_f32_16x16x32_bf16 v[66:69], v[188:191], v[230:233], v[66:69]
	v_mfma_f32_16x16x32_bf16 v[82:85], v[180:183], v[230:233], v[82:85]
	v_mfma_f32_16x16x32_bf16 v[138:141], v[184:187], v[200:203], v[138:141]
	v_mfma_f32_16x16x32_bf16 v[130:133], v[192:195], v[200:203], v[130:133]
	v_mfma_f32_16x16x32_bf16 v[114:117], v[192:195], v[208:211], v[114:117]
	v_mfma_f32_16x16x32_bf16 v[122:125], v[184:187], v[208:211], v[122:125]
	v_mfma_f32_16x16x32_bf16 v[106:109], v[184:187], v[216:219], v[106:109]
	v_mfma_f32_16x16x32_bf16 v[98:101], v[192:195], v[216:219], v[98:101]
	v_mfma_f32_16x16x32_bf16 v[66:69], v[192:195], v[238:241], v[66:69]
	v_mfma_f32_16x16x32_bf16 v[82:85], v[184:187], v[238:241], v[82:85]
	s_setprio 0
	s_barrier
	s_add_i32 s0, s0, s37
	v_lshl_add_u64 v[168:169], v[168:169], 0, s[76:77]
	s_mov_b32 m0, s0
	ds_read_b128 v[196:199], v177 offset:49152
	ds_read_b128 v[200:203], v177 offset:50176
	ds_read_b128 v[204:207], v177 offset:51200
	ds_read_b128 v[208:211], v177 offset:52224
	ds_read_b128 v[212:215], v177 offset:53248
	ds_read_b128 v[216:219], v177 offset:54272
	ds_read_b128 v[230:233], v177 offset:55296
	ds_read_b128 v[238:241], v177 offset:56320
	global_load_lds_dwordx4 v[168:169], off
	s_add_i32 m0, s0, 0x2000
	s_add_u32 s56, s56, 0x40080
	v_lshl_add_u64 v[168:169], v[242:243], 0, s[76:77]
	s_addc_u32 s57, s57, 0
	s_add_i32 s0, s83, s37
	global_load_lds_dwordx4 v[168:169], off
	v_lshl_add_u64 v[168:169], s[56:57], 0, v[150:151]
	s_mov_b32 m0, s0
	s_nop 0
	global_load_lds_dwordx4 v[168:169], off
	v_lshl_add_u64 v[168:169], s[56:57], 0, v[146:147]
	s_add_i32 m0, s0, 0x2000
	s_nop 0
	global_load_lds_dwordx4 v[168:169], off
	v_lshl_add_u64 v[168:169], v[244:245], 0, s[76:77]
	s_mov_b32 m0, s67
	s_nop 0
	global_load_lds_dwordx4 v[168:169], off
	v_lshl_add_u64 v[168:169], v[246:247], 0, s[76:77]
	s_mov_b32 m0, s68
	s_nop 0
	global_load_lds_dwordx4 v[168:169], off
	s_waitcnt vmcnt(8)
	s_waitcnt lgkmcnt(0)
	s_barrier
	s_setprio 1
	s_waitcnt lgkmcnt(0)
	v_mfma_f32_16x16x32_bf16 v[62:65], v[74:77], v[196:199], v[62:65]
	v_mfma_f32_16x16x32_bf16 v[54:57], v[90:93], v[196:199], v[54:57]
	v_mfma_f32_16x16x32_bf16 v[38:41], v[90:93], v[204:207], v[38:41]
	v_mfma_f32_16x16x32_bf16 v[46:49], v[74:77], v[204:207], v[46:49]
	v_mfma_f32_16x16x32_bf16 v[30:33], v[74:77], v[212:215], v[30:33]
	v_mfma_f32_16x16x32_bf16 v[22:25], v[90:93], v[212:215], v[22:25]
	v_mfma_f32_16x16x32_bf16 v[6:9], v[90:93], v[230:233], v[6:9]
	v_mfma_f32_16x16x32_bf16 v[14:17], v[74:77], v[230:233], v[14:17]
	v_mfma_f32_16x16x32_bf16 v[62:65], v[78:81], v[200:203], v[62:65]
	v_mfma_f32_16x16x32_bf16 v[54:57], v[94:97], v[200:203], v[54:57]
	v_mfma_f32_16x16x32_bf16 v[38:41], v[94:97], v[208:211], v[38:41]
	v_mfma_f32_16x16x32_bf16 v[46:49], v[78:81], v[208:211], v[46:49]
	v_mfma_f32_16x16x32_bf16 v[30:33], v[78:81], v[216:219], v[30:33]
	v_mfma_f32_16x16x32_bf16 v[22:25], v[94:97], v[216:219], v[22:25]
	v_mfma_f32_16x16x32_bf16 v[6:9], v[94:97], v[238:241], v[6:9]
	v_mfma_f32_16x16x32_bf16 v[14:17], v[78:81], v[238:241], v[14:17]
	s_setprio 0
	s_setprio 1
	v_mfma_f32_16x16x32_bf16 v[58:61], v[180:183], v[196:199], v[58:61]
	v_mfma_f32_16x16x32_bf16 v[50:53], v[188:191], v[196:199], v[50:53]
	v_mfma_f32_16x16x32_bf16 v[34:37], v[188:191], v[204:207], v[34:37]
	v_mfma_f32_16x16x32_bf16 v[42:45], v[180:183], v[204:207], v[42:45]
	v_mfma_f32_16x16x32_bf16 v[26:29], v[180:183], v[212:215], v[26:29]
	v_mfma_f32_16x16x32_bf16 v[18:21], v[188:191], v[212:215], v[18:21]
	v_mfma_f32_16x16x32_bf16 v[2:5], v[188:191], v[230:233], v[2:5]
	v_mfma_f32_16x16x32_bf16 v[10:13], v[180:183], v[230:233], v[10:13]
	v_mfma_f32_16x16x32_bf16 v[58:61], v[184:187], v[200:203], v[58:61]
	v_mfma_f32_16x16x32_bf16 v[50:53], v[192:195], v[200:203], v[50:53]
	v_mfma_f32_16x16x32_bf16 v[34:37], v[192:195], v[208:211], v[34:37]
	v_mfma_f32_16x16x32_bf16 v[42:45], v[184:187], v[208:211], v[42:45]
	v_mfma_f32_16x16x32_bf16 v[26:29], v[184:187], v[216:219], v[26:29]
	v_mfma_f32_16x16x32_bf16 v[18:21], v[192:195], v[216:219], v[18:21]
	v_mfma_f32_16x16x32_bf16 v[2:5], v[192:195], v[238:241], v[2:5]
	v_mfma_f32_16x16x32_bf16 v[10:13], v[184:187], v[238:241], v[10:13]
	s_setprio 0
	s_barrier
	s_add_i32 s82, s82, 2
	s_add_u32 s52, s52, 0x100
	s_addc_u32 s53, s53, 0
	s_add_u32 s73, s73, 0x100
	s_addc_u32 s75, s75, 0

.LBB0_263:
	v_readlane_b32 s4, v254, 2
	v_readlane_b32 s5, v254, 3
	s_andn2_b64 vcc, exec, s[4:5]
	s_cbranch_vccnz .LBB0_272
	v_readlane_b32 s4, v254, 17
	v_mov_b32_e32 v16, v220
	v_readlane_b32 s5, v254, 18
	s_andn2_b64 vcc, exec, s[4:5]
	v_readfirstlane_b32 s15, v16
	s_cbranch_vccnz .LBB0_272
	v_lshlrev_b32_e32 v2, 4, v16
	v_add_u32_e32 v3, 0x2000, v2
	v_ashrrev_i32_e32 v4, 31, v3
	v_lshrrev_b32_e32 v4, 22, v4
	v_add_u32_e32 v4, v3, v4
	v_ashrrev_i32_e32 v12, 10, v4
	v_mul_i32_i24_e32 v4, 0x400, v12
	v_sub_u32_e32 v3, v3, v4
	v_lshrrev_b32_e32 v4, 4, v3
	v_bitop3_b32 v3, v4, v3, 32 bitop3:0x6c
	v_ashrrev_i32_e32 v4, 31, v3
	v_lshrrev_b32_e32 v4, 26, v4
	v_add_u32_e32 v4, v3, v4
	v_lshlrev_b32_e32 v5, 3, v12
	v_ashrrev_i32_e32 v13, 6, v4
	v_and_b32_e32 v5, -16, v5
	v_add_u32_e32 v5, v13, v5
	v_and_b32_e32 v6, 3, v13
	s_mov_b32 s4, 0x1fffe0
	v_lshrrev_b32_e32 v7, 2, v5
	v_lshlrev_b32_e32 v8, 1, v5
	v_and_b32_e32 v4, 0xc0, v4
	v_and_or_b32 v6, v5, s4, v6
	v_and_b32_e32 v7, 4, v7
	v_and_b32_e32 v8, 24, v8
	v_sub_u32_e32 v3, v3, v4
	v_or3_b32 v6, v6, v7, v8
	v_lshlrev_b32_e32 v7, 5, v12
	v_ashrrev_i16_sdwa v3, v235, sext(v3) dst_sel:DWORD dst_unused:UNUSED_PAD src0_sel:DWORD src1_sel:BYTE_0
	v_and_b32_e32 v7, 32, v7
	v_bfe_i32 v14, v3, 0, 16
	v_add_lshl_u32 v3, v7, v14, 1
	v_lshl_add_u32 v46, v6, 11, v3
	v_lshl_add_u32 v48, v5, 11, v3
	v_bfe_i32 v3, v16, 27, 1
	v_lshrrev_b32_e32 v3, 22, v3
	v_add_u32_e32 v3, v2, v3
	v_and_b32_e32 v3, 0xfffffc00, v3
	v_sub_u32_e32 v2, v2, v3
	v_lshrrev_b32_e32 v3, 4, v2
	v_ashrrev_i32_e32 v4, 31, v16
	v_bitop3_b32 v2, v3, v2, 32 bitop3:0x6c
	v_lshrrev_b32_e32 v4, 26, v4
	v_ashrrev_i32_e32 v3, 31, v2
	v_add_u32_e32 v4, v16, v4
	v_lshrrev_b32_e32 v3, 26, v3
	v_ashrrev_i32_e32 v17, 6, v4
	v_add_u32_e32 v3, v2, v3
	v_lshlrev_b32_e32 v4, 3, v17
	v_ashrrev_i32_e32 v15, 6, v3
	v_and_b32_e32 v4, -16, v4
	v_add_u32_e32 v4, v15, v4
	v_and_b32_e32 v5, 3, v15
	v_lshrrev_b32_e32 v6, 2, v4
	v_lshlrev_b32_e32 v7, 1, v4
	v_and_b32_e32 v3, 0xc0, v3
	v_and_or_b32 v5, v4, s4, v5
	v_and_b32_e32 v6, 4, v6
	v_and_b32_e32 v7, 24, v7
	v_sub_u32_e32 v2, v2, v3
	v_or3_b32 v5, v5, v6, v7
	v_lshlrev_b32_e32 v6, 5, v17
	v_ashrrev_i16_sdwa v2, v235, sext(v2) dst_sel:DWORD dst_unused:UNUSED_PAD src0_sel:DWORD src1_sel:BYTE_0
	v_and_b32_e32 v6, 32, v6
	v_bfe_i32 v19, v2, 0, 16
	v_mov_b32_e32 v3, s88
	s_ashr_i32 s0, s15, 6
	s_ashr_i32 s3, s15, 8
	v_add_lshl_u32 v2, v6, v19, 1
	ds_read_b32 v3, v3
	v_mov_b32_e32 v6, s89
	s_and_b32 s14, s0, 3
	s_lshl_b32 s20, s0, 10
	s_lshl_b32 s8, s3, 6
	ds_read_b32 v6, v6
	v_readlane_b32 s4, v254, 7
	v_readlane_b32 s5, v254, 8
	s_add_u32 s4, s35, s4
	s_mul_hi_u32 s6, s74, 0xaaaaaaab
	s_addc_u32 s5, s36, s5
	s_lshr_b32 s10, s6, 1
	s_mul_i32 s6, s10, 3
	s_waitcnt lgkmcnt(0)
	v_readfirstlane_b32 s13, v3
	s_sub_i32 s21, s74, s6
	s_mul_i32 s6, s74, 0x18000
	v_readfirstlane_b32 s12, v6
	s_add_u32 s6, s13, s6
	v_readlane_b32 s9, v254, 9
	s_addc_u32 s7, s12, 0
	s_lshl_b32 s9, s9, 2
	s_add_u32 s11, s6, s9
	s_addc_u32 s35, s7, 0
	s_ashr_i32 s9, s8, 31
	s_lshl_b64 s[6:7], s[8:9], 2
	s_add_u32 s6, s11, s6
	s_mul_i32 s46, s10, 0xfa00
	s_addc_u32 s7, s35, s7
	s_lshl_b64 s[10:11], s[46:47], 2
	s_add_u32 s9, s13, s10
	s_addc_u32 s10, s12, s11
	s_cmp_eq_u32 s21, 1
	s_movk_i32 s11, 0x6e00
	s_cselect_b32 s11, s11, 0x8c00
	s_cmp_lg_u32 s21, 0
	s_cselect_b32 s11, s11, 0
	s_lshl_b32 s11, s11, 2
	s_add_u32 s9, s9, s11
	s_addc_u32 s10, s10, 0
	v_readlane_b32 s12, v254, 63
	v_readlane_b32 s13, v255, 0
	s_add_u32 s9, s9, s12
	s_addc_u32 s11, s10, s13
	s_lshl_b32 s10, s14, 7
	v_lshl_add_u32 v50, v5, 11, v2
	v_lshl_add_u32 v52, v4, 11, v2
	s_add_u32 s10, s9, s10
	v_lshlrev_b32_e32 v2, 1, v16
	s_addc_u32 s11, s11, 0
	v_and_b32_e32 v2, 0x60, v2
	v_mov_b32_e32 v3, v0
	v_lshlrev_b32_e32 v4, 6, v16
	v_lshl_add_u64 v[2:3], s[10:11], 0, v[2:3]
	v_and_b32_e32 v4, 0x200, v4
	v_mov_b32_e32 v5, v0
	v_lshl_add_u64 v[2:3], v[2:3], 0, v[4:5]
	v_and_b32_e32 v4, 7, v16
	v_lshlrev_b32_e32 v4, 2, v4
	v_and_b32_e32 v18, 48, v16
	v_lshl_add_u64 v[2:3], v[2:3], 0, v[4:5]
	s_mov_b64 s[10:11], 0x10416000
	v_and_b32_e32 v1, 15, v16
	v_lshl_add_u64 v[4:5], v[2:3], 0, s[10:11]
	v_lshlrev_b32_e32 v2, 2, v18
	v_mov_b32_e32 v3, v0
	s_mulk_i32 s0, 0x300
	v_lshl_add_u64 v[6:7], s[6:7], 0, v[2:3]
	v_lshlrev_b32_e32 v2, 2, v1
	s_add_i32 s0, s0, 0
	v_lshl_add_u64 v[6:7], v[6:7], 0, v[2:3]
	s_mov_b64 s[6:7], 0x310000
	s_add_i32 m0, s0, 0x20400
	v_lshl_add_u64 v[8:9], v[6:7], 0, s[6:7]
	s_mov_b64 s[6:7], 0x310200
	global_load_lds_dword v[8:9], off
	v_lshl_add_u64 v[6:7], v[6:7], 0, s[6:7]
	s_add_i32 m0, s0, 0x20500
	s_add_i32 s35, s20, 0
	global_load_lds_dword v[6:7], off
	s_add_i32 m0, s0, 0x20600
	v_readlane_b32 s0, v254, 6
	global_load_lds_dword v[4:5], off
	s_add_i32 m0, s35, 0x10000
	v_mov_b32_e32 v51, v0
	s_add_i32 m0, s35, 0x12000
	s_add_u32 s6, s4, 0x40000
	s_addc_u32 s7, s5, 0
	s_add_i32 m0, s35, 0x14000
	v_mov_b32_e32 v47, v0
	s_add_i32 m0, s35, 0x16000
	v_mov_b32_e32 v53, v0
	s_add_u32 s6, s31, s0
	s_addc_u32 s7, s34, 0
	s_mov_b32 m0, s35
	s_add_i32 s31, s35, 0x2000
	s_mov_b32 m0, s31
	s_add_i32 s34, s35, 0x4000
	s_mov_b32 m0, s34
	s_add_i32 s36, s35, 0x6000
	s_mov_b32 m0, s36
	v_mov_b32_e32 v49, v0
	v_lshl_add_u64 v[10:11], s[4:5], 0, v[50:51]
	v_lshl_add_u64 v[8:9], s[4:5], 0, v[46:47]
	v_lshl_add_u64 v[6:7], s[6:7], 0, v[52:53]
	s_cmp_lg_u32 s3, 1
	v_lshl_add_u64 v[4:5], s[6:7], 0, v[48:49]
	s_cbranch_scc1 .LBB0_267
	s_barrier
.LBB0_267:
	v_or_b32_e32 v82, s8, v1
	v_and_b32_e32 v66, 63, v16
	v_lshlrev_b32_e32 v3, 6, v82
	s_movk_i32 s0, 0x3c0
	v_lshlrev_b32_e32 v16, 2, v82
	v_and_or_b32 v3, v3, s0, v18
	s_lshl_b32 s0, s3, 13
	v_and_b32_e32 v16, 32, v16
	v_bitop3_b32 v16, v3, s0, v16 bitop3:0xde
	v_lshl_or_b32 v3, v1, 6, v18
	s_lshl_b32 s0, s14, 12
	v_and_b32_e32 v2, 32, v2
	v_bitop3_b32 v67, v3, s0, v2 bitop3:0xde
	s_add_i32 m0, s35, 0x18000
	v_lshl_add_u64 v[2:3], v[10:11], 0, s[76:77]
	s_lshl_b32 s21, s14, 5
	s_waitcnt vmcnt(2)
	s_barrier
	v_lshl_add_u64 v[2:3], v[8:9], 0, s[76:77]
	s_add_i32 m0, s35, 0x1a000
	s_add_i32 s37, s35, 0x8000
	s_add_i32 s38, s35, 0xa000
	v_lshl_add_u64 v[2:3], v[6:7], 0, s[76:77]
	s_mov_b32 m0, s37
	s_add_u32 s8, s4, 0x40080
	v_lshl_add_u64 v[2:3], v[4:5], 0, s[76:77]
	s_mov_b32 m0, s38
	s_addc_u32 s9, s5, 0
	s_add_i32 m0, s35, 0x1c000
	v_lshl_add_u64 v[2:3], s[8:9], 0, v[50:51]
	v_lshl_add_u64 v[2:3], s[8:9], 0, v[46:47]
	s_add_i32 m0, s35, 0x1e000
	v_readlane_b32 s0, v254, 53
	v_lshlrev_b32_e32 v2, 14, v12
	v_and_b32_e32 v2, 0xffff8000, v2
	v_lshl_add_u32 v2, v13, 11, v2
	v_and_b32_e32 v3, 1, v12
	s_add_u32 s8, s26, s0
	v_lshl_or_b32 v2, v3, 6, v2
	s_addc_u32 s9, s1, 0
	v_lshl_add_u32 v2, v14, 1, v2
	v_mov_b32_e32 v3, v0
	v_lshl_add_u64 v[62:63], s[8:9], 0, v[2:3]
	v_lshlrev_b32_e32 v2, 14, v17
	v_and_b32_e32 v2, 0xffff8000, v2
	v_lshl_add_u32 v2, v15, 11, v2
	v_and_b32_e32 v3, 1, v17
	v_readlane_b32 s0, v254, 52
	v_lshl_or_b32 v2, v3, 6, v2
	s_add_u32 s40, s26, s0
	v_lshl_add_u32 v2, v19, 1, v2
	v_mov_b32_e32 v3, v0
	s_addc_u32 s41, s1, 0
	v_readlane_b32 s0, v254, 54
	v_lshl_add_u64 v[64:65], s[8:9], 0, v[2:3]
	s_add_u32 s0, s26, s0
	v_readlane_b32 s8, v254, 55
	s_addc_u32 s8, s1, s8
	s_add_u32 s1, s27, s30
	s_waitcnt vmcnt(6)
	s_addc_u32 s9, 0, 0
	s_add_u32 s1, s0, s1
	s_addc_u32 s26, s8, s9
	s_mov_b32 s27, -2
	s_mov_b64 s[8:9], 0
	v_add_u32_e32 v68, 0, v16
	s_barrier
	s_movk_i32 s8, 0x100
	s_movk_i32 s9, 0x800
	s_mov_b32 s27, 0
	v_add_u32_e32 v156, 0x10000, v67
	v_add_u32_e32 v157, 0x21c00, v67
	s_add_u32 s10, s4, s8
	s_addc_u32 s11, s5, 0
	s_add_u32 s12, s10, 0x40000
	s_addc_u32 s13, s11, 0
	s_add_u32 s42, s6, s8
	s_addc_u32 s43, s7, 0
	s_addk_i32 s8, 0x80
	s_cmp_eq_u32 s8, s9
	s_cselect_b32 s8, 0, s8
	s_add_i32 m0, s35, 0xc000
	ds_read_b128 v[84:87], v156 offset:0
	ds_read_b128 v[88:91], v156 offset:1024
	ds_read_b128 v[92:95], v156 offset:2048
	ds_read_b128 v[96:99], v156 offset:3072
	global_load_lds_dwordx4 v50, s[10:11]
	s_add_i32 m0, s35, 0xe000
	ds_read_b128 v[116:119], v68 offset:0
	ds_read_b128 v[120:123], v68 offset:1024
	ds_read_b128 v[124:127], v68 offset:2048
	global_load_lds_dwordx4 v46, s[10:11]
	s_add_i32 m0, s35, 0x21c00
	ds_read_b128 v[128:131], v68 offset:3072
	ds_read_b128 v[132:135], v68 offset:4096
	ds_read_b128 v[136:139], v68 offset:5120
	global_load_lds_dwordx4 v50, s[12:13]
	s_add_i32 m0, s35, 0x23c00
	ds_read_b128 v[140:143], v68 offset:6144
	ds_read_b128 v[144:147], v68 offset:7168
	global_load_lds_dwordx4 v46, s[12:13]
	s_add_i32 m0, s35, 0x4000
	ds_read_b128 v[100:103], v156 offset:16384
	ds_read_b128 v[104:107], v156 offset:17408
	global_load_lds_dwordx4 v52, s[42:43]
	s_add_i32 m0, s35, 0x6000
	ds_read_b128 v[108:111], v156 offset:18432
	ds_read_b128 v[112:115], v156 offset:19456
	global_load_lds_dwordx4 v48, s[42:43]
	s_waitcnt vmcnt(6)
	s_waitcnt lgkmcnt(0)
	s_barrier
	s_setprio 1
	v_mfma_f32_16x16x32_bf16 v[78:81], v[84:87], v[116:119], 0
	v_mfma_f32_16x16x32_bf16 v[70:73], v[92:95], v[116:119], 0
	v_mfma_f32_16x16x32_bf16 v[54:57], v[84:87], v[124:127], 0
	s_add_u32 s10, s4, s8
	v_mfma_f32_16x16x32_bf16 v[38:41], v[92:95], v[124:127], 0
	s_addc_u32 s11, s5, 0
	v_mfma_f32_16x16x32_bf16 v[30:33], v[84:87], v[132:135], 0
	s_add_u32 s12, s10, 0x40000
	v_mfma_f32_16x16x32_bf16 v[22:25], v[92:95], v[132:135], 0
	s_addc_u32 s13, s11, 0
	v_mfma_f32_16x16x32_bf16 v[14:17], v[84:87], v[140:143], 0
	s_add_u32 s42, s6, s8
	v_mfma_f32_16x16x32_bf16 v[6:9], v[92:95], v[140:143], 0
	s_addc_u32 s43, s7, 0
	v_mfma_f32_16x16x32_bf16 v[78:81], v[88:91], v[120:123], v[78:81]
	s_addk_i32 s8, 0x80
	v_mfma_f32_16x16x32_bf16 v[70:73], v[96:99], v[120:123], v[70:73]
	s_cmp_eq_u32 s8, s9
	v_mfma_f32_16x16x32_bf16 v[54:57], v[88:91], v[128:131], v[54:57]
	s_cselect_b32 s8, 0, s8
	v_mfma_f32_16x16x32_bf16 v[38:41], v[96:99], v[128:131], v[38:41]
	v_mfma_f32_16x16x32_bf16 v[30:33], v[88:91], v[136:139], v[30:33]
	v_mfma_f32_16x16x32_bf16 v[22:25], v[96:99], v[136:139], v[22:25]
	v_mfma_f32_16x16x32_bf16 v[14:17], v[88:91], v[144:147], v[14:17]
	v_mfma_f32_16x16x32_bf16 v[6:9], v[96:99], v[144:147], v[6:9]
	v_mfma_f32_16x16x32_bf16 v[74:77], v[100:103], v[116:119], 0
	v_mfma_f32_16x16x32_bf16 v[58:61], v[108:111], v[116:119], 0
	v_mfma_f32_16x16x32_bf16 v[42:45], v[100:103], v[124:127], 0
	v_mfma_f32_16x16x32_bf16 v[34:37], v[108:111], v[124:127], 0
	v_mfma_f32_16x16x32_bf16 v[26:29], v[100:103], v[132:135], 0
	v_mfma_f32_16x16x32_bf16 v[18:21], v[108:111], v[132:135], 0
	v_mfma_f32_16x16x32_bf16 v[10:13], v[100:103], v[140:143], 0
	v_mfma_f32_16x16x32_bf16 v[2:5], v[108:111], v[140:143], 0
	v_mfma_f32_16x16x32_bf16 v[74:77], v[104:107], v[120:123], v[74:77]
	v_mfma_f32_16x16x32_bf16 v[58:61], v[112:115], v[120:123], v[58:61]
	v_mfma_f32_16x16x32_bf16 v[42:45], v[104:107], v[128:131], v[42:45]
	v_mfma_f32_16x16x32_bf16 v[34:37], v[112:115], v[128:131], v[34:37]
	v_mfma_f32_16x16x32_bf16 v[26:29], v[104:107], v[136:139], v[26:29]
	v_mfma_f32_16x16x32_bf16 v[18:21], v[112:115], v[136:139], v[18:21]
	v_mfma_f32_16x16x32_bf16 v[10:13], v[104:107], v[144:147], v[10:13]
	v_mfma_f32_16x16x32_bf16 v[2:5], v[112:115], v[144:147], v[2:5]
	s_setprio 0
	s_barrier
	s_add_i32 s27, s27, 1
